# ssm block loops: ds_write2 for the transpose and hbuf stores, next block's 8 MFMAs issued right after the current block's LDS writes
# speedup vs baseline: 1.0012x; 1.0012x over previous
.LBB0_791:
	s_add_i32 s3, s2, -3
	s_min_i32 s4, s3, 0x80
	s_lshl_b32 s4, s4, 4
	s_add_i32 s4, s4, s34
	v_or_b32_e32 v8, s4, v37
	s_add_i32 s4, s2, -2
	s_min_i32 s4, s4, 0x80
	s_lshl_b32 s4, s4, 4
	v_ashrrev_i32_e32 v9, 31, v8
	s_add_i32 s4, s4, s34
	v_lshlrev_b64 v[8:9], 10, v[8:9]
	s_cmp_lg_u32 s2, 2
	v_lshl_add_u64 v[8:9], v[62:63], 0, v[8:9]
	s_cselect_b32 s4, s4, 0x8000
	global_load_dwordx2 v[70:71], v[8:9], off
	v_or_b32_e32 v8, s4, v37
	v_ashrrev_i32_e32 v9, 31, v8
	v_lshlrev_b64 v[8:9], 10, v[8:9]
	v_lshl_add_u64 v[8:9], v[62:63], 0, v[8:9]
	global_load_dwordx2 v[74:75], v[8:9], off
	v_sub_co_u32_e64 v8, s[40:41], s2, 1
	v_min_i32_e32 v8, 0x80, v8
	v_lshlrev_b32_e32 v8, 4, v8
	v_add_u32_e32 v8, s34, v8
	s_min_i32 s4, s2, 0x80
	v_or_b32_e32 v8, v8, v37
	s_lshl_b32 s4, s4, 4
	v_ashrrev_i32_e32 v9, 31, v8
	s_add_i32 s4, s4, s34
	v_lshlrev_b64 v[8:9], 10, v[8:9]
	s_and_b64 s[40:41], s[40:41], exec
	v_lshl_add_u64 v[8:9], v[62:63], 0, v[8:9]
	s_cselect_b32 s4, 0x8000, s4
	global_load_dwordx2 v[76:77], v[8:9], off
	v_or_b32_e32 v8, s4, v37
	v_ashrrev_i32_e32 v9, 31, v8
	v_lshlrev_b64 v[8:9], 10, v[8:9]
	v_lshl_add_u64 v[8:9], v[62:63], 0, v[8:9]
	global_load_dwordx2 v[78:79], v[8:9], off
	v_add_u32_e32 v238, 0x900, v41
	v_add_u32_e32 v239, 0x1200, v41
	v_add_u32_e32 v240, 0x1b00, v41
	s_waitcnt vmcnt(4)
	v_mfma_f32_16x16x16_bf16 v[112:115], v[26:27], v[6:7], 0
	v_mfma_f32_16x16x16_bf16 v[116:119], v[28:29], v[6:7], 0
	v_mfma_f32_16x16x16_bf16 v[120:123], v[30:31], v[6:7], 0
	v_mfma_f32_16x16x16_bf16 v[124:127], v[52:53], v[6:7], 0
	v_mfma_f32_16x16x16_bf16 v[128:131], v[54:55], v[6:7], 0
	v_mfma_f32_16x16x16_bf16 v[132:135], v[56:57], v[6:7], 0
	v_mfma_f32_16x16x16_bf16 v[136:139], v[58:59], v[6:7], 0
	v_mfma_f32_16x16x16_bf16 v[140:143], v[60:61], v[6:7], 0
	s_nop 7
	ds_write2_b32 v41, v112, v116 offset1:16
	ds_write2_b32 v41, v113, v117 offset0:36 offset1:52
	ds_write2_b32 v41, v114, v118 offset0:72 offset1:88
	ds_write2_b32 v41, v115, v119 offset0:108 offset1:124
	ds_write2_b32 v238, v120, v124 offset1:16
	ds_write2_b32 v238, v121, v125 offset0:36 offset1:52
	ds_write2_b32 v238, v122, v126 offset0:72 offset1:88
	ds_write2_b32 v238, v123, v127 offset0:108 offset1:124
	ds_write2_b32 v239, v128, v132 offset1:16
	ds_write2_b32 v239, v129, v133 offset0:36 offset1:52
	ds_write2_b32 v239, v130, v134 offset0:72 offset1:88
	ds_write2_b32 v239, v131, v135 offset0:108 offset1:124
	ds_write2_b32 v240, v136, v140 offset1:16
	ds_write2_b32 v240, v137, v141 offset0:36 offset1:52
	ds_write2_b32 v240, v138, v142 offset0:72 offset1:88
	ds_write2_b32 v240, v139, v143 offset0:108 offset1:124
	s_nop 1
	v_mfma_f32_16x16x16_bf16 v[112:115], v[26:27], v[2:3], 0
	v_mfma_f32_16x16x16_bf16 v[116:119], v[28:29], v[2:3], 0
	v_mfma_f32_16x16x16_bf16 v[120:123], v[30:31], v[2:3], 0
	v_mfma_f32_16x16x16_bf16 v[124:127], v[52:53], v[2:3], 0
	v_mfma_f32_16x16x16_bf16 v[128:131], v[54:55], v[2:3], 0
	v_mfma_f32_16x16x16_bf16 v[132:135], v[56:57], v[2:3], 0
	v_mfma_f32_16x16x16_bf16 v[136:139], v[58:59], v[2:3], 0
	v_mfma_f32_16x16x16_bf16 v[140:143], v[60:61], v[2:3], 0
	s_waitcnt lgkmcnt(0)
	ds_read_b128 v[206:209], v89
	ds_read_b128 v[210:213], v89 offset:16
	ds_read_b128 v[214:217], v89 offset:32
	ds_read_b128 v[218:221], v89 offset:48
	ds_read_b128 v[222:225], v89 offset:64
	ds_read_b128 v[226:229], v89 offset:80
	ds_read_b128 v[230:233], v89 offset:96
	ds_read_b128 v[234:237], v89 offset:112
	s_waitcnt lgkmcnt(3)
	v_mul_f32_e32 v204, v48, v0
	v_mul_f32_e32 v205, v48, v1
	v_fma_f32 v204, v50, v1, -v204
	v_fma_f32 v205, v50, v0, v205
	v_add_f32_e32 v1, v206, v204
	v_add_f32_e32 v0, v222, v205
	v_mul_f32_e32 v204, v48, v0
	v_mul_f32_e32 v205, v48, v1
	v_fma_f32 v204, v50, v1, -v204
	v_fma_f32 v205, v50, v0, v205
	v_add_f32_e32 v1, v207, v204
	v_add_f32_e32 v0, v223, v205
	v_mul_f32_e32 v204, v48, v0
	v_mul_f32_e32 v205, v48, v1
	v_fma_f32 v204, v50, v1, -v204
	v_fma_f32 v205, v50, v0, v205
	v_add_f32_e32 v1, v208, v204
	v_add_f32_e32 v0, v224, v205
	v_mul_f32_e32 v204, v48, v0
	v_mul_f32_e32 v205, v48, v1
	v_fma_f32 v204, v50, v1, -v204
	v_fma_f32 v205, v50, v0, v205
	v_add_f32_e32 v1, v209, v204
	v_add_f32_e32 v0, v225, v205
	s_waitcnt lgkmcnt(2)
	v_mul_f32_e32 v204, v48, v0
	v_mul_f32_e32 v205, v48, v1
	v_fma_f32 v204, v50, v1, -v204
	v_fma_f32 v205, v50, v0, v205
	v_add_f32_e32 v1, v210, v204
	v_add_f32_e32 v0, v226, v205
	v_mul_f32_e32 v204, v48, v0
	v_mul_f32_e32 v205, v48, v1
	v_fma_f32 v204, v50, v1, -v204
	v_fma_f32 v205, v50, v0, v205
	v_add_f32_e32 v1, v211, v204
	v_add_f32_e32 v0, v227, v205
	v_mul_f32_e32 v204, v48, v0
	v_mul_f32_e32 v205, v48, v1
	v_fma_f32 v204, v50, v1, -v204
	v_fma_f32 v205, v50, v0, v205
	v_add_f32_e32 v1, v212, v204
	v_add_f32_e32 v0, v228, v205
	v_mul_f32_e32 v204, v48, v0
	v_mul_f32_e32 v205, v48, v1
	v_fma_f32 v204, v50, v1, -v204
	v_fma_f32 v205, v50, v0, v205
	v_add_f32_e32 v1, v213, v204
	v_add_f32_e32 v0, v229, v205
	s_waitcnt lgkmcnt(1)
	v_mul_f32_e32 v204, v48, v0
	v_mul_f32_e32 v205, v48, v1
	v_fma_f32 v204, v50, v1, -v204
	v_fma_f32 v205, v50, v0, v205
	v_add_f32_e32 v1, v214, v204
	v_add_f32_e32 v0, v230, v205
	v_mul_f32_e32 v204, v48, v0
	v_mul_f32_e32 v205, v48, v1
	v_fma_f32 v204, v50, v1, -v204
	v_fma_f32 v205, v50, v0, v205
	v_add_f32_e32 v1, v215, v204
	v_add_f32_e32 v0, v231, v205
	v_mul_f32_e32 v204, v48, v0
	v_mul_f32_e32 v205, v48, v1
	v_fma_f32 v204, v50, v1, -v204
	v_fma_f32 v205, v50, v0, v205
	v_add_f32_e32 v1, v216, v204
	v_add_f32_e32 v0, v232, v205
	v_mul_f32_e32 v204, v48, v0
	v_mul_f32_e32 v205, v48, v1
	v_fma_f32 v204, v50, v1, -v204
	v_fma_f32 v205, v50, v0, v205
	v_add_f32_e32 v1, v217, v204
	v_add_f32_e32 v0, v233, v205
	s_waitcnt lgkmcnt(0)
	v_mul_f32_e32 v204, v48, v0
	v_mul_f32_e32 v205, v48, v1
	v_fma_f32 v204, v50, v1, -v204
	v_fma_f32 v205, v50, v0, v205
	v_add_f32_e32 v1, v218, v204
	v_add_f32_e32 v0, v234, v205
	v_mul_f32_e32 v204, v48, v0
	v_mul_f32_e32 v205, v48, v1
	v_fma_f32 v204, v50, v1, -v204
	v_fma_f32 v205, v50, v0, v205
	v_add_f32_e32 v1, v219, v204
	v_add_f32_e32 v0, v235, v205
	v_mul_f32_e32 v204, v48, v0
	v_mul_f32_e32 v205, v48, v1
	v_fma_f32 v204, v50, v1, -v204
	v_fma_f32 v205, v50, v0, v205
	v_add_f32_e32 v1, v220, v204
	v_add_f32_e32 v0, v236, v205
	v_mul_f32_e32 v204, v48, v0
	v_mul_f32_e32 v205, v48, v1
	v_fma_f32 v204, v50, v1, -v204
	v_fma_f32 v205, v50, v0, v205
	v_add_f32_e32 v1, v221, v204
	v_add_f32_e32 v0, v237, v205
	ds_write2_b32 v41, v112, v116 offset1:16
	ds_write2_b32 v41, v113, v117 offset0:36 offset1:52
	ds_write2_b32 v41, v114, v118 offset0:72 offset1:88
	ds_write2_b32 v41, v115, v119 offset0:108 offset1:124
	ds_write2_b32 v238, v120, v124 offset1:16
	ds_write2_b32 v238, v121, v125 offset0:36 offset1:52
	ds_write2_b32 v238, v122, v126 offset0:72 offset1:88
	ds_write2_b32 v238, v123, v127 offset0:108 offset1:124
	ds_write2_b32 v239, v128, v132 offset1:16
	ds_write2_b32 v239, v129, v133 offset0:36 offset1:52
	ds_write2_b32 v239, v130, v134 offset0:72 offset1:88
	ds_write2_b32 v239, v131, v135 offset0:108 offset1:124
	ds_write2_b32 v240, v136, v140 offset1:16
	ds_write2_b32 v240, v137, v141 offset0:36 offset1:52
	ds_write2_b32 v240, v138, v142 offset0:72 offset1:88
	ds_write2_b32 v240, v139, v143 offset0:108 offset1:124
	s_nop 1
	v_mfma_f32_16x16x16_bf16 v[112:115], v[26:27], v[4:5], 0
	v_mfma_f32_16x16x16_bf16 v[116:119], v[28:29], v[4:5], 0
	v_mfma_f32_16x16x16_bf16 v[120:123], v[30:31], v[4:5], 0
	v_mfma_f32_16x16x16_bf16 v[124:127], v[52:53], v[4:5], 0
	v_mfma_f32_16x16x16_bf16 v[128:131], v[54:55], v[4:5], 0
	v_mfma_f32_16x16x16_bf16 v[132:135], v[56:57], v[4:5], 0
	v_mfma_f32_16x16x16_bf16 v[136:139], v[58:59], v[4:5], 0
	v_mfma_f32_16x16x16_bf16 v[140:143], v[60:61], v[4:5], 0
	s_waitcnt lgkmcnt(0)
	ds_read_b128 v[206:209], v89
	ds_read_b128 v[210:213], v89 offset:16
	ds_read_b128 v[214:217], v89 offset:32
	ds_read_b128 v[218:221], v89 offset:48
	ds_read_b128 v[222:225], v89 offset:64
	ds_read_b128 v[226:229], v89 offset:80
	ds_read_b128 v[230:233], v89 offset:96
	ds_read_b128 v[234:237], v89 offset:112
	s_waitcnt lgkmcnt(3)
	v_mul_f32_e32 v204, v48, v0
	v_mul_f32_e32 v205, v48, v1
	v_fma_f32 v204, v50, v1, -v204
	v_fma_f32 v205, v50, v0, v205
	v_add_f32_e32 v1, v206, v204
	v_add_f32_e32 v0, v222, v205
	v_mul_f32_e32 v204, v48, v0
	v_mul_f32_e32 v205, v48, v1
	v_fma_f32 v204, v50, v1, -v204
	v_fma_f32 v205, v50, v0, v205
	v_add_f32_e32 v1, v207, v204
	v_add_f32_e32 v0, v223, v205
	v_mul_f32_e32 v204, v48, v0
	v_mul_f32_e32 v205, v48, v1
	v_fma_f32 v204, v50, v1, -v204
	v_fma_f32 v205, v50, v0, v205
	v_add_f32_e32 v1, v208, v204
	v_add_f32_e32 v0, v224, v205
	v_mul_f32_e32 v204, v48, v0
	v_mul_f32_e32 v205, v48, v1
	v_fma_f32 v204, v50, v1, -v204
	v_fma_f32 v205, v50, v0, v205
	v_add_f32_e32 v1, v209, v204
	v_add_f32_e32 v0, v225, v205
	s_waitcnt lgkmcnt(2)
	v_mul_f32_e32 v204, v48, v0
	v_mul_f32_e32 v205, v48, v1
	v_fma_f32 v204, v50, v1, -v204
	v_fma_f32 v205, v50, v0, v205
	v_add_f32_e32 v1, v210, v204
	v_add_f32_e32 v0, v226, v205
	v_mul_f32_e32 v204, v48, v0
	v_mul_f32_e32 v205, v48, v1
	v_fma_f32 v204, v50, v1, -v204
	v_fma_f32 v205, v50, v0, v205
	v_add_f32_e32 v1, v211, v204
	v_add_f32_e32 v0, v227, v205
	v_mul_f32_e32 v204, v48, v0
	v_mul_f32_e32 v205, v48, v1
	v_fma_f32 v204, v50, v1, -v204
	v_fma_f32 v205, v50, v0, v205
	v_add_f32_e32 v1, v212, v204
	v_add_f32_e32 v0, v228, v205
	v_mul_f32_e32 v204, v48, v0
	v_mul_f32_e32 v205, v48, v1
	v_fma_f32 v204, v50, v1, -v204
	v_fma_f32 v205, v50, v0, v205
	v_add_f32_e32 v1, v213, v204
	v_add_f32_e32 v0, v229, v205
	s_waitcnt lgkmcnt(1)
	v_mul_f32_e32 v204, v48, v0
	v_mul_f32_e32 v205, v48, v1
	v_fma_f32 v204, v50, v1, -v204
	v_fma_f32 v205, v50, v0, v205
	v_add_f32_e32 v1, v214, v204
	v_add_f32_e32 v0, v230, v205
	v_mul_f32_e32 v204, v48, v0
	v_mul_f32_e32 v205, v48, v1
	v_fma_f32 v204, v50, v1, -v204
	v_fma_f32 v205, v50, v0, v205
	v_add_f32_e32 v1, v215, v204
	v_add_f32_e32 v0, v231, v205
	v_mul_f32_e32 v204, v48, v0
	v_mul_f32_e32 v205, v48, v1
	v_fma_f32 v204, v50, v1, -v204
	v_fma_f32 v205, v50, v0, v205
	v_add_f32_e32 v1, v216, v204
	v_add_f32_e32 v0, v232, v205
	v_mul_f32_e32 v204, v48, v0
	v_mul_f32_e32 v205, v48, v1
	v_fma_f32 v204, v50, v1, -v204
	v_fma_f32 v205, v50, v0, v205
	v_add_f32_e32 v1, v217, v204
	v_add_f32_e32 v0, v233, v205
	s_waitcnt lgkmcnt(0)
	v_mul_f32_e32 v204, v48, v0
	v_mul_f32_e32 v205, v48, v1
	v_fma_f32 v204, v50, v1, -v204
	v_fma_f32 v205, v50, v0, v205
	v_add_f32_e32 v1, v218, v204
	v_add_f32_e32 v0, v234, v205
	v_mul_f32_e32 v204, v48, v0
	v_mul_f32_e32 v205, v48, v1
	v_fma_f32 v204, v50, v1, -v204
	v_fma_f32 v205, v50, v0, v205
	v_add_f32_e32 v1, v219, v204
	v_add_f32_e32 v0, v235, v205
	v_mul_f32_e32 v204, v48, v0
	v_mul_f32_e32 v205, v48, v1
	v_fma_f32 v204, v50, v1, -v204
	v_fma_f32 v205, v50, v0, v205
	v_add_f32_e32 v1, v220, v204
	v_add_f32_e32 v0, v236, v205
	v_mul_f32_e32 v204, v48, v0
	v_mul_f32_e32 v205, v48, v1
	v_fma_f32 v204, v50, v1, -v204
	v_fma_f32 v205, v50, v0, v205
	v_add_f32_e32 v1, v221, v204
	v_add_f32_e32 v0, v237, v205
	ds_write2_b32 v41, v112, v116 offset1:16
	ds_write2_b32 v41, v113, v117 offset0:36 offset1:52
	ds_write2_b32 v41, v114, v118 offset0:72 offset1:88
	ds_write2_b32 v41, v115, v119 offset0:108 offset1:124
	ds_write2_b32 v238, v120, v124 offset1:16
	ds_write2_b32 v238, v121, v125 offset0:36 offset1:52
	ds_write2_b32 v238, v122, v126 offset0:72 offset1:88
	ds_write2_b32 v238, v123, v127 offset0:108 offset1:124
	ds_write2_b32 v239, v128, v132 offset1:16
	ds_write2_b32 v239, v129, v133 offset0:36 offset1:52
	ds_write2_b32 v239, v130, v134 offset0:72 offset1:88
	ds_write2_b32 v239, v131, v135 offset0:108 offset1:124
	ds_write2_b32 v240, v136, v140 offset1:16
	ds_write2_b32 v240, v137, v141 offset0:36 offset1:52
	ds_write2_b32 v240, v138, v142 offset0:72 offset1:88
	ds_write2_b32 v240, v139, v143 offset0:108 offset1:124
	s_nop 1
	v_mfma_f32_16x16x16_bf16 v[112:115], v[26:27], v[68:69], 0
	v_mfma_f32_16x16x16_bf16 v[116:119], v[28:29], v[68:69], 0
	v_mfma_f32_16x16x16_bf16 v[120:123], v[30:31], v[68:69], 0
	v_mfma_f32_16x16x16_bf16 v[124:127], v[52:53], v[68:69], 0
	v_mfma_f32_16x16x16_bf16 v[128:131], v[54:55], v[68:69], 0
	v_mfma_f32_16x16x16_bf16 v[132:135], v[56:57], v[68:69], 0
	v_mfma_f32_16x16x16_bf16 v[136:139], v[58:59], v[68:69], 0
	v_mfma_f32_16x16x16_bf16 v[140:143], v[60:61], v[68:69], 0
	s_waitcnt lgkmcnt(0)
	ds_read_b128 v[206:209], v89
	ds_read_b128 v[210:213], v89 offset:16
	ds_read_b128 v[214:217], v89 offset:32
	ds_read_b128 v[218:221], v89 offset:48
	ds_read_b128 v[222:225], v89 offset:64
	ds_read_b128 v[226:229], v89 offset:80
	ds_read_b128 v[230:233], v89 offset:96
	ds_read_b128 v[234:237], v89 offset:112
	s_waitcnt lgkmcnt(3)
	v_mul_f32_e32 v204, v48, v0
	v_mul_f32_e32 v205, v48, v1
	v_fma_f32 v204, v50, v1, -v204
	v_fma_f32 v205, v50, v0, v205
	v_add_f32_e32 v1, v206, v204
	v_add_f32_e32 v0, v222, v205
	v_mul_f32_e32 v204, v48, v0
	v_mul_f32_e32 v205, v48, v1
	v_fma_f32 v204, v50, v1, -v204
	v_fma_f32 v205, v50, v0, v205
	v_add_f32_e32 v1, v207, v204
	v_add_f32_e32 v0, v223, v205
	v_mul_f32_e32 v204, v48, v0
	v_mul_f32_e32 v205, v48, v1
	v_fma_f32 v204, v50, v1, -v204
	v_fma_f32 v205, v50, v0, v205
	v_add_f32_e32 v1, v208, v204
	v_add_f32_e32 v0, v224, v205
	v_mul_f32_e32 v204, v48, v0
	v_mul_f32_e32 v205, v48, v1
	v_fma_f32 v204, v50, v1, -v204
	v_fma_f32 v205, v50, v0, v205
	v_add_f32_e32 v1, v209, v204
	v_add_f32_e32 v0, v225, v205
	s_waitcnt lgkmcnt(2)
	v_mul_f32_e32 v204, v48, v0
	v_mul_f32_e32 v205, v48, v1
	v_fma_f32 v204, v50, v1, -v204
	v_fma_f32 v205, v50, v0, v205
	v_add_f32_e32 v1, v210, v204
	v_add_f32_e32 v0, v226, v205
	v_mul_f32_e32 v204, v48, v0
	v_mul_f32_e32 v205, v48, v1
	v_fma_f32 v204, v50, v1, -v204
	v_fma_f32 v205, v50, v0, v205
	v_add_f32_e32 v1, v211, v204
	v_add_f32_e32 v0, v227, v205
	v_mul_f32_e32 v204, v48, v0
	v_mul_f32_e32 v205, v48, v1
	v_fma_f32 v204, v50, v1, -v204
	v_fma_f32 v205, v50, v0, v205
	v_add_f32_e32 v1, v212, v204
	v_add_f32_e32 v0, v228, v205
	v_mul_f32_e32 v204, v48, v0
	v_mul_f32_e32 v205, v48, v1
	v_fma_f32 v204, v50, v1, -v204
	v_fma_f32 v205, v50, v0, v205
	v_add_f32_e32 v1, v213, v204
	v_add_f32_e32 v0, v229, v205
	s_waitcnt lgkmcnt(1)
	v_mul_f32_e32 v204, v48, v0
	v_mul_f32_e32 v205, v48, v1
	v_fma_f32 v204, v50, v1, -v204
	v_fma_f32 v205, v50, v0, v205
	v_add_f32_e32 v1, v214, v204
	v_add_f32_e32 v0, v230, v205
	v_mul_f32_e32 v204, v48, v0
	v_mul_f32_e32 v205, v48, v1
	v_fma_f32 v204, v50, v1, -v204
	v_fma_f32 v205, v50, v0, v205
	v_add_f32_e32 v1, v215, v204
	v_add_f32_e32 v0, v231, v205
	v_mul_f32_e32 v204, v48, v0
	v_mul_f32_e32 v205, v48, v1
	v_fma_f32 v204, v50, v1, -v204
	v_fma_f32 v205, v50, v0, v205
	v_add_f32_e32 v1, v216, v204
	v_add_f32_e32 v0, v232, v205
	v_mul_f32_e32 v204, v48, v0
	v_mul_f32_e32 v205, v48, v1
	v_fma_f32 v204, v50, v1, -v204
	v_fma_f32 v205, v50, v0, v205
	v_add_f32_e32 v1, v217, v204
	v_add_f32_e32 v0, v233, v205
	s_waitcnt lgkmcnt(0)
	v_mul_f32_e32 v204, v48, v0
	v_mul_f32_e32 v205, v48, v1
	v_fma_f32 v204, v50, v1, -v204
	v_fma_f32 v205, v50, v0, v205
	v_add_f32_e32 v1, v218, v204
	v_add_f32_e32 v0, v234, v205
	v_mul_f32_e32 v204, v48, v0
	v_mul_f32_e32 v205, v48, v1
	v_fma_f32 v204, v50, v1, -v204
	v_fma_f32 v205, v50, v0, v205
	v_add_f32_e32 v1, v219, v204
	v_add_f32_e32 v0, v235, v205
	v_mul_f32_e32 v204, v48, v0
	v_mul_f32_e32 v205, v48, v1
	v_fma_f32 v204, v50, v1, -v204
	v_fma_f32 v205, v50, v0, v205
	v_add_f32_e32 v1, v220, v204
	v_add_f32_e32 v0, v236, v205
	v_mul_f32_e32 v204, v48, v0
	v_mul_f32_e32 v205, v48, v1
	v_fma_f32 v204, v50, v1, -v204
	v_fma_f32 v205, v50, v0, v205
	v_add_f32_e32 v1, v221, v204
	v_add_f32_e32 v0, v237, v205
	ds_write2_b32 v41, v112, v116 offset1:16
	ds_write2_b32 v41, v113, v117 offset0:36 offset1:52
	ds_write2_b32 v41, v114, v118 offset0:72 offset1:88
	ds_write2_b32 v41, v115, v119 offset0:108 offset1:124
	ds_write2_b32 v238, v120, v124 offset1:16
	ds_write2_b32 v238, v121, v125 offset0:36 offset1:52
	ds_write2_b32 v238, v122, v126 offset0:72 offset1:88
	ds_write2_b32 v238, v123, v127 offset0:108 offset1:124
	ds_write2_b32 v239, v128, v132 offset1:16
	ds_write2_b32 v239, v129, v133 offset0:36 offset1:52
	ds_write2_b32 v239, v130, v134 offset0:72 offset1:88
	ds_write2_b32 v239, v131, v135 offset0:108 offset1:124
	ds_write2_b32 v240, v136, v140 offset1:16
	ds_write2_b32 v240, v137, v141 offset0:36 offset1:52
	ds_write2_b32 v240, v138, v142 offset0:72 offset1:88
	ds_write2_b32 v240, v139, v143 offset0:108 offset1:124
	s_waitcnt lgkmcnt(0)
	ds_read_b128 v[206:209], v89
	ds_read_b128 v[210:213], v89 offset:16
	ds_read_b128 v[214:217], v89 offset:32
	ds_read_b128 v[218:221], v89 offset:48
	ds_read_b128 v[222:225], v89 offset:64
	ds_read_b128 v[226:229], v89 offset:80
	ds_read_b128 v[230:233], v89 offset:96
	ds_read_b128 v[234:237], v89 offset:112
	s_waitcnt lgkmcnt(3)
	v_mul_f32_e32 v204, v48, v0
	v_mul_f32_e32 v205, v48, v1
	v_fma_f32 v204, v50, v1, -v204
	v_fma_f32 v205, v50, v0, v205
	v_add_f32_e32 v1, v206, v204
	v_add_f32_e32 v0, v222, v205
	v_mul_f32_e32 v204, v48, v0
	v_mul_f32_e32 v205, v48, v1
	v_fma_f32 v204, v50, v1, -v204
	v_fma_f32 v205, v50, v0, v205
	v_add_f32_e32 v1, v207, v204
	v_add_f32_e32 v0, v223, v205
	v_mul_f32_e32 v204, v48, v0
	v_mul_f32_e32 v205, v48, v1
	v_fma_f32 v204, v50, v1, -v204
	v_fma_f32 v205, v50, v0, v205
	v_add_f32_e32 v1, v208, v204
	v_add_f32_e32 v0, v224, v205
	v_mul_f32_e32 v204, v48, v0
	v_mul_f32_e32 v205, v48, v1
	v_fma_f32 v204, v50, v1, -v204
	v_fma_f32 v205, v50, v0, v205
	v_add_f32_e32 v1, v209, v204
	v_add_f32_e32 v0, v225, v205
	s_waitcnt lgkmcnt(2)
	v_mul_f32_e32 v204, v48, v0
	v_mul_f32_e32 v205, v48, v1
	v_fma_f32 v204, v50, v1, -v204
	v_fma_f32 v205, v50, v0, v205
	v_add_f32_e32 v1, v210, v204
	v_add_f32_e32 v0, v226, v205
	v_mul_f32_e32 v204, v48, v0
	v_mul_f32_e32 v205, v48, v1
	v_fma_f32 v204, v50, v1, -v204
	v_fma_f32 v205, v50, v0, v205
	v_add_f32_e32 v1, v211, v204
	v_add_f32_e32 v0, v227, v205
	v_mul_f32_e32 v204, v48, v0
	v_mul_f32_e32 v205, v48, v1
	v_fma_f32 v204, v50, v1, -v204
	v_fma_f32 v205, v50, v0, v205
	v_add_f32_e32 v1, v212, v204
	v_add_f32_e32 v0, v228, v205
	v_mul_f32_e32 v204, v48, v0
	v_mul_f32_e32 v205, v48, v1
	v_fma_f32 v204, v50, v1, -v204
	v_fma_f32 v205, v50, v0, v205
	v_add_f32_e32 v1, v213, v204
	v_add_f32_e32 v0, v229, v205
	s_waitcnt lgkmcnt(1)
	v_mul_f32_e32 v204, v48, v0
	v_mul_f32_e32 v205, v48, v1
	v_fma_f32 v204, v50, v1, -v204
	v_fma_f32 v205, v50, v0, v205
	v_add_f32_e32 v1, v214, v204
	v_add_f32_e32 v0, v230, v205
	v_mul_f32_e32 v204, v48, v0
	v_mul_f32_e32 v205, v48, v1
	v_fma_f32 v204, v50, v1, -v204
	v_fma_f32 v205, v50, v0, v205
	v_add_f32_e32 v1, v215, v204
	v_add_f32_e32 v0, v231, v205
	v_mul_f32_e32 v204, v48, v0
	v_mul_f32_e32 v205, v48, v1
	v_fma_f32 v204, v50, v1, -v204
	v_fma_f32 v205, v50, v0, v205
	v_add_f32_e32 v1, v216, v204
	v_add_f32_e32 v0, v232, v205
	v_mul_f32_e32 v204, v48, v0
	v_mul_f32_e32 v205, v48, v1
	v_fma_f32 v204, v50, v1, -v204
	v_fma_f32 v205, v50, v0, v205
	v_add_f32_e32 v1, v217, v204
	v_add_f32_e32 v0, v233, v205
	s_waitcnt lgkmcnt(0)
	v_mul_f32_e32 v204, v48, v0
	v_mul_f32_e32 v205, v48, v1
	v_fma_f32 v204, v50, v1, -v204
	v_fma_f32 v205, v50, v0, v205
	v_add_f32_e32 v1, v218, v204
	v_add_f32_e32 v0, v234, v205
	v_mul_f32_e32 v204, v48, v0
	v_mul_f32_e32 v205, v48, v1
	v_fma_f32 v204, v50, v1, -v204
	v_fma_f32 v205, v50, v0, v205
	v_add_f32_e32 v1, v219, v204
	v_add_f32_e32 v0, v235, v205
	v_mul_f32_e32 v204, v48, v0
	v_mul_f32_e32 v205, v48, v1
	v_fma_f32 v204, v50, v1, -v204
	v_fma_f32 v205, v50, v0, v205
	v_add_f32_e32 v1, v220, v204
	v_add_f32_e32 v0, v236, v205
	v_mul_f32_e32 v204, v48, v0
	v_mul_f32_e32 v205, v48, v1
	v_fma_f32 v204, v50, v1, -v204
	v_fma_f32 v205, v50, v0, v205
	v_add_f32_e32 v1, v221, v204
	v_add_f32_e32 v0, v237, v205
	s_waitcnt vmcnt(0)
	v_mov_b32_e32 v6, v70
	v_mov_b32_e32 v7, v71
	v_mov_b32_e32 v2, v74
	v_mov_b32_e32 v3, v75
	v_mov_b32_e32 v4, v76
	v_mov_b32_e32 v5, v77
	v_mov_b32_e32 v68, v78
	v_mov_b32_e32 v69, v79
	s_add_i32 s2, s2, 4
	s_cmp_lt_i32 s3, s1
	s_cbranch_scc1 .LBB0_791
	s_branch .LBB0_774

.LBB0_915:
	s_add_i32 s36, s34, 4
	s_min_i32 s2, s36, 0x80
	s_lshl_b32 s2, s2, 4
	s_add_i32 s2, s2, s30
	s_cmp_lg_u32 s34, -4
	s_cselect_b32 s2, s2, 0x8000
	v_or_b32_e32 v20, s2, v121
	s_add_i32 s2, s34, 5
	s_min_i32 s2, s2, 0x80
	s_lshl_b32 s2, s2, 4
	s_add_i32 s2, s2, s30
	v_ashrrev_i32_e32 v21, 31, v20
	s_cmp_lg_u32 s34, -5
	v_lshlrev_b64 v[20:21], 10, v[20:21]
	s_cselect_b32 s2, s2, 0x8000
	v_lshl_add_u64 v[80:81], v[24:25], 0, v[20:21]
	v_or_b32_e32 v20, s2, v121
	s_add_i32 s2, s34, 6
	s_min_i32 s2, s2, 0x80
	s_lshl_b32 s2, s2, 4
	s_add_i32 s2, s2, s30
	v_ashrrev_i32_e32 v21, 31, v20
	s_cmp_lg_u32 s34, -6
	v_lshlrev_b64 v[20:21], 10, v[20:21]
	s_cselect_b32 s2, s2, 0x8000
	v_lshl_add_u64 v[82:83], v[24:25], 0, v[20:21]
	v_or_b32_e32 v20, s2, v121
	s_add_i32 s2, s34, 7
	s_min_i32 s2, s2, 0x80
	s_lshl_b32 s2, s2, 4
	s_add_i32 s2, s2, s30
	s_cmp_lg_u32 s34, -7
	s_cselect_b32 s2, s2, 0x8000
	v_or_b32_e32 v84, s2, v121
	v_ashrrev_i32_e32 v21, 31, v20
	v_ashrrev_i32_e32 v85, 31, v84
	v_lshlrev_b64 v[20:21], 10, v[20:21]
	v_lshlrev_b64 v[84:85], 10, v[84:85]
	v_lshl_add_u64 v[116:117], v[24:25], 0, v[20:21]
	v_lshl_add_u64 v[118:119], v[24:25], 0, v[84:85]
	global_load_dwordx2 v[86:87], v[80:81], off
	global_load_dwordx2 v[84:85], v[82:83], off
	global_load_dwordx2 v[82:83], v[116:117], off
	global_load_dwordx2 v[80:81], v[118:119], off
	s_waitcnt vmcnt(4)
	v_mfma_f32_16x16x16_bf16 v[204:207], v[28:29], v[92:93], 0
	v_mfma_f32_16x16x16_bf16 v[208:211], v[30:31], v[92:93], 0
	v_mfma_f32_16x16x16_bf16 v[212:215], v[66:67], v[92:93], 0
	v_mfma_f32_16x16x16_bf16 v[216:219], v[68:69], v[92:93], 0
	v_mfma_f32_16x16x16_bf16 v[220:223], v[70:71], v[92:93], 0
	v_mfma_f32_16x16x16_bf16 v[224:227], v[72:73], v[92:93], 0
	v_mfma_f32_16x16x16_bf16 v[228:231], v[74:75], v[92:93], 0
	v_mfma_f32_16x16x16_bf16 v[232:235], v[76:77], v[92:93], 0
	s_nop 7
	ds_write2_b32 v96, v204, v208 offset1:16
	ds_write2_b32 v96, v205, v209 offset0:36 offset1:52
	ds_write2_b32 v96, v206, v210 offset0:72 offset1:88
	ds_write2_b32 v96, v207, v211 offset0:108 offset1:124
	ds_write2_b32 v100, v212, v216 offset0:64 offset1:80
	ds_write2_b32 v100, v213, v217 offset0:100 offset1:116
	ds_write2_b32 v100, v214, v218 offset0:136 offset1:152
	ds_write2_b32 v100, v215, v219 offset0:172 offset1:188
	ds_write2_b32 v101, v220, v224 offset0:128 offset1:144
	ds_write2_b32 v101, v221, v225 offset0:164 offset1:180
	ds_write2_b32 v101, v222, v226 offset0:200 offset1:216
	ds_write2_b32 v101, v223, v227 offset0:236 offset1:252
	ds_write2_b32 v102, v228, v232 offset0:192 offset1:208
	ds_write2_b32 v102, v229, v233 offset0:228 offset1:244
	ds_write2_b32 v103, v230, v234 offset0:8 offset1:24
	ds_write2_b32 v103, v231, v235 offset0:44 offset1:60
	s_nop 1
	v_mfma_f32_16x16x16_bf16 v[204:207], v[28:29], v[90:91], 0
	v_mfma_f32_16x16x16_bf16 v[208:211], v[30:31], v[90:91], 0
	v_mfma_f32_16x16x16_bf16 v[212:215], v[66:67], v[90:91], 0
	v_mfma_f32_16x16x16_bf16 v[216:219], v[68:69], v[90:91], 0
	v_mfma_f32_16x16x16_bf16 v[220:223], v[70:71], v[90:91], 0
	v_mfma_f32_16x16x16_bf16 v[224:227], v[72:73], v[90:91], 0
	v_mfma_f32_16x16x16_bf16 v[228:231], v[74:75], v[90:91], 0
	v_mfma_f32_16x16x16_bf16 v[232:235], v[76:77], v[90:91], 0
	s_waitcnt lgkmcnt(0)
	ds_read_b128 v[236:239], v49
	ds_read_b128 v[240:243], v49 offset:16
	ds_read_b128 v[244:247], v49 offset:32
	ds_read_b128 v[248:251], v49 offset:48
	ds_read_b128 v[158:161], v49 offset:64
	ds_read_b128 v[162:165], v49 offset:80
	ds_read_b128 v[166:169], v49 offset:96
	ds_read_b128 v[170:173], v49 offset:112
	s_waitcnt lgkmcnt(3)
	v_mul_f32_e32 v252, v60, v65
	v_mul_f32_e32 v253, v60, v64
	v_fma_f32 v252, v62, v64, -v252
	v_fma_f32 v253, v62, v65, v253
	v_add_f32_e32 v64, v236, v252
	v_add_f32_e32 v65, v158, v253
	v_cvt_pk_bf16_f32 v202, v64, v65
	v_mul_f32_e32 v252, v60, v65
	v_mul_f32_e32 v253, v60, v64
	v_fma_f32 v252, v62, v64, -v252
	v_fma_f32 v253, v62, v65, v253
	v_add_f32_e32 v64, v237, v252
	v_add_f32_e32 v65, v159, v253
	v_cvt_pk_bf16_f32 v203, v64, v65
	ds_write2_b32 v104, v202, v203 offset1:68
	v_mul_f32_e32 v252, v60, v65
	v_mul_f32_e32 v253, v60, v64
	v_fma_f32 v252, v62, v64, -v252
	v_fma_f32 v253, v62, v65, v253
	v_add_f32_e32 v64, v238, v252
	v_add_f32_e32 v65, v160, v253
	v_cvt_pk_bf16_f32 v202, v64, v65
	v_mul_f32_e32 v252, v60, v65
	v_mul_f32_e32 v253, v60, v64
	v_fma_f32 v252, v62, v64, -v252
	v_fma_f32 v253, v62, v65, v253
	v_add_f32_e32 v64, v239, v252
	v_add_f32_e32 v65, v161, v253
	v_cvt_pk_bf16_f32 v203, v64, v65
	ds_write2_b32 v104, v202, v203 offset0:136 offset1:204
	s_waitcnt lgkmcnt(4)
	v_mul_f32_e32 v252, v60, v65
	v_mul_f32_e32 v253, v60, v64
	v_fma_f32 v252, v62, v64, -v252
	v_fma_f32 v253, v62, v65, v253
	v_add_f32_e32 v64, v240, v252
	v_add_f32_e32 v65, v162, v253
	v_cvt_pk_bf16_f32 v202, v64, v65
	v_mul_f32_e32 v252, v60, v65
	v_mul_f32_e32 v253, v60, v64
	v_fma_f32 v252, v62, v64, -v252
	v_fma_f32 v253, v62, v65, v253
	v_add_f32_e32 v64, v241, v252
	v_add_f32_e32 v65, v163, v253
	v_cvt_pk_bf16_f32 v203, v64, v65
	ds_write2_b32 v105, v202, v203 offset0:16 offset1:84
	v_mul_f32_e32 v252, v60, v65
	v_mul_f32_e32 v253, v60, v64
	v_fma_f32 v252, v62, v64, -v252
	v_fma_f32 v253, v62, v65, v253
	v_add_f32_e32 v64, v242, v252
	v_add_f32_e32 v65, v164, v253
	v_cvt_pk_bf16_f32 v202, v64, v65
	v_mul_f32_e32 v252, v60, v65
	v_mul_f32_e32 v253, v60, v64
	v_fma_f32 v252, v62, v64, -v252
	v_fma_f32 v253, v62, v65, v253
	v_add_f32_e32 v64, v243, v252
	v_add_f32_e32 v65, v165, v253
	v_cvt_pk_bf16_f32 v203, v64, v65
	ds_write2_b32 v105, v202, v203 offset0:152 offset1:220
	s_waitcnt lgkmcnt(5)
	v_mul_f32_e32 v252, v60, v65
	v_mul_f32_e32 v253, v60, v64
	v_fma_f32 v252, v62, v64, -v252
	v_fma_f32 v253, v62, v65, v253
	v_add_f32_e32 v64, v244, v252
	v_add_f32_e32 v65, v166, v253
	v_cvt_pk_bf16_f32 v202, v64, v65
	v_mul_f32_e32 v252, v60, v65
	v_mul_f32_e32 v253, v60, v64
	v_fma_f32 v252, v62, v64, -v252
	v_fma_f32 v253, v62, v65, v253
	v_add_f32_e32 v64, v245, v252
	v_add_f32_e32 v65, v167, v253
	v_cvt_pk_bf16_f32 v203, v64, v65
	ds_write2_b32 v106, v202, v203 offset0:32 offset1:100
	v_mul_f32_e32 v252, v60, v65
	v_mul_f32_e32 v253, v60, v64
	v_fma_f32 v252, v62, v64, -v252
	v_fma_f32 v253, v62, v65, v253
	v_add_f32_e32 v64, v246, v252
	v_add_f32_e32 v65, v168, v253
	v_cvt_pk_bf16_f32 v202, v64, v65
	v_mul_f32_e32 v252, v60, v65
	v_mul_f32_e32 v253, v60, v64
	v_fma_f32 v252, v62, v64, -v252
	v_fma_f32 v253, v62, v65, v253
	v_add_f32_e32 v64, v247, v252
	v_add_f32_e32 v65, v169, v253
	v_cvt_pk_bf16_f32 v203, v64, v65
	ds_write2_b32 v106, v202, v203 offset0:168 offset1:236
	s_waitcnt lgkmcnt(6)
	v_mul_f32_e32 v252, v60, v65
	v_mul_f32_e32 v253, v60, v64
	v_fma_f32 v252, v62, v64, -v252
	v_fma_f32 v253, v62, v65, v253
	v_add_f32_e32 v64, v248, v252
	v_add_f32_e32 v65, v170, v253
	v_cvt_pk_bf16_f32 v202, v64, v65
	v_mul_f32_e32 v252, v60, v65
	v_mul_f32_e32 v253, v60, v64
	v_fma_f32 v252, v62, v64, -v252
	v_fma_f32 v253, v62, v65, v253
	v_add_f32_e32 v64, v249, v252
	v_add_f32_e32 v65, v171, v253
	v_cvt_pk_bf16_f32 v203, v64, v65
	ds_write2_b32 v107, v202, v203 offset0:48 offset1:116
	v_mul_f32_e32 v252, v60, v65
	v_mul_f32_e32 v253, v60, v64
	v_fma_f32 v252, v62, v64, -v252
	v_fma_f32 v253, v62, v65, v253
	v_add_f32_e32 v64, v250, v252
	v_add_f32_e32 v65, v172, v253
	v_cvt_pk_bf16_f32 v202, v64, v65
	v_mul_f32_e32 v252, v60, v65
	v_mul_f32_e32 v253, v60, v64
	v_fma_f32 v252, v62, v64, -v252
	v_fma_f32 v253, v62, v65, v253
	v_add_f32_e32 v64, v251, v252
	v_add_f32_e32 v65, v173, v253
	v_cvt_pk_bf16_f32 v203, v64, v65
	ds_write2_b32 v107, v202, v203 offset0:184 offset1:252
	s_cmp_gt_i32 s34, 0
	s_cselect_b64 s[2:3], -1, 0
	s_or_b64 s[2:3], s[0:1], s[2:3]
	s_and_b64 vcc, exec, s[2:3]
	s_waitcnt lgkmcnt(0)
	ds_read_b128 v[20:23], v99 offset:9216
	ds_read_b128 v[108:111], v99 offset:9280
	s_waitcnt lgkmcnt(1)
	v_mfma_f32_16x16x32_bf16 v[20:23], v[0:3], v[20:23], 0
	s_waitcnt lgkmcnt(0)
	v_mfma_f32_16x16x32_bf16 v[20:23], v[4:7], v[108:111], v[20:23]
	ds_read_b128 v[108:111], v99 offset:9344
	ds_read_b128 v[112:115], v99 offset:9408
	s_waitcnt lgkmcnt(1)
	v_mfma_f32_16x16x32_bf16 v[20:23], v[8:11], v[108:111], v[20:23]
	s_waitcnt lgkmcnt(0)
	v_mfma_f32_16x16x32_bf16 v[20:23], v[12:15], v[112:115], v[20:23]
	s_cbranch_vccz .LBB0_917
	v_lshlrev_b32_e32 v108, 16, v93
	v_and_b32_e32 v109, 0xffff0000, v93
	s_nop 4
	v_pk_fma_f32 v[22:23], v[18:19], v[108:109], v[22:23]
	s_add_i32 s2, s35, -16
	v_mul_f32_e32 v93, 0x3d372713, v23
	v_mul_f32_e32 v93, v23, v93
	v_fma_f32 v93, v23, v93, v23
	v_mul_f32_e32 v93, 0x3fcc422a, v93
	v_mul_f32_e32 v93, 0xbfb8aa3b, v93
	v_exp_f32_e32 v93, v93
	s_cmp_lg_u32 s34, 0
	s_cselect_b32 s2, s2, 0x8000
	v_add_f32_e32 v93, 1.0, v93
	v_rcp_f32_e32 v109, v93
	v_mul_f32_e32 v93, 0x3d372713, v22
	v_mul_f32_e32 v93, v22, v93
	v_fma_f32 v93, v22, v93, v22
	v_mul_f32_e32 v93, 0x3fcc422a, v93
	v_mul_f32_e32 v93, 0xbfb8aa3b, v93
	v_exp_f32_e32 v93, v93
	s_nop 0
	v_add_f32_e32 v93, 1.0, v93
	v_rcp_f32_e32 v108, v93
	s_nop 0
	v_pk_mul_f32 v[22:23], v[22:23], v[108:109]
	v_lshlrev_b32_e32 v108, 16, v92
	v_and_b32_e32 v109, 0xffff0000, v92
	v_pk_fma_f32 v[20:21], v[16:17], v[108:109], v[20:21]
	s_nop 0
	v_mul_f32_e32 v92, 0x3d372713, v21
	v_mul_f32_e32 v92, v21, v92
	v_fma_f32 v92, v21, v92, v21
	v_mul_f32_e32 v92, 0x3fcc422a, v92
	v_mul_f32_e32 v92, 0xbfb8aa3b, v92
	v_exp_f32_e32 v92, v92
	s_nop 0
	v_add_f32_e32 v92, 1.0, v92
	v_rcp_f32_e32 v93, v92
	v_mul_f32_e32 v92, 0x3d372713, v20
	v_mul_f32_e32 v92, v20, v92
	v_fma_f32 v92, v20, v92, v20
	v_mul_f32_e32 v92, 0x3fcc422a, v92
	v_mul_f32_e32 v92, 0xbfb8aa3b, v92
	v_exp_f32_e32 v92, v92
	s_nop 0
	v_add_f32_e32 v92, 1.0, v92
	v_rcp_f32_e32 v92, v92
	s_nop 0
	v_pk_mul_f32 v[20:21], v[20:21], v[92:93]
	v_or_b32_e32 v92, s2, v121
	v_ashrrev_i32_e32 v93, 31, v92
	v_lshlrev_b64 v[92:93], 10, v[92:93]
	v_lshl_add_u64 v[92:93], v[26:27], 0, v[92:93]
	v_cvt_pk_bf16_f32 v20, v20, v21
	v_cvt_pk_bf16_f32 v21, v22, v23
	global_store_dwordx2 v[92:93], v[20:21], off
.LBB0_917:
	ds_write2_b32 v96, v204, v208 offset1:16
	ds_write2_b32 v96, v205, v209 offset0:36 offset1:52
	ds_write2_b32 v96, v206, v210 offset0:72 offset1:88
	ds_write2_b32 v96, v207, v211 offset0:108 offset1:124
	ds_write2_b32 v100, v212, v216 offset0:64 offset1:80
	ds_write2_b32 v100, v213, v217 offset0:100 offset1:116
	ds_write2_b32 v100, v214, v218 offset0:136 offset1:152
	ds_write2_b32 v100, v215, v219 offset0:172 offset1:188
	ds_write2_b32 v101, v220, v224 offset0:128 offset1:144
	ds_write2_b32 v101, v221, v225 offset0:164 offset1:180
	ds_write2_b32 v101, v222, v226 offset0:200 offset1:216
	ds_write2_b32 v101, v223, v227 offset0:236 offset1:252
	ds_write2_b32 v102, v228, v232 offset0:192 offset1:208
	ds_write2_b32 v102, v229, v233 offset0:228 offset1:244
	ds_write2_b32 v103, v230, v234 offset0:8 offset1:24
	ds_write2_b32 v103, v231, v235 offset0:44 offset1:60
	s_nop 1
	v_mfma_f32_16x16x16_bf16 v[204:207], v[28:29], v[88:89], 0
	v_mfma_f32_16x16x16_bf16 v[208:211], v[30:31], v[88:89], 0
	v_mfma_f32_16x16x16_bf16 v[212:215], v[66:67], v[88:89], 0
	v_mfma_f32_16x16x16_bf16 v[216:219], v[68:69], v[88:89], 0
	v_mfma_f32_16x16x16_bf16 v[220:223], v[70:71], v[88:89], 0
	v_mfma_f32_16x16x16_bf16 v[224:227], v[72:73], v[88:89], 0
	v_mfma_f32_16x16x16_bf16 v[228:231], v[74:75], v[88:89], 0
	v_mfma_f32_16x16x16_bf16 v[232:235], v[76:77], v[88:89], 0
	s_waitcnt lgkmcnt(0)
	ds_read_b128 v[236:239], v49
	ds_read_b128 v[240:243], v49 offset:16
	ds_read_b128 v[244:247], v49 offset:32
	ds_read_b128 v[248:251], v49 offset:48
	ds_read_b128 v[158:161], v49 offset:64
	ds_read_b128 v[162:165], v49 offset:80
	ds_read_b128 v[166:169], v49 offset:96
	ds_read_b128 v[170:173], v49 offset:112
	s_waitcnt lgkmcnt(3)
	v_mul_f32_e32 v252, v60, v65
	v_mul_f32_e32 v253, v60, v64
	v_fma_f32 v252, v62, v64, -v252
	v_fma_f32 v253, v62, v65, v253
	v_add_f32_e32 v64, v236, v252
	v_add_f32_e32 v65, v158, v253
	v_cvt_pk_bf16_f32 v202, v64, v65
	v_mul_f32_e32 v252, v60, v65
	v_mul_f32_e32 v253, v60, v64
	v_fma_f32 v252, v62, v64, -v252
	v_fma_f32 v253, v62, v65, v253
	v_add_f32_e32 v64, v237, v252
	v_add_f32_e32 v65, v159, v253
	v_cvt_pk_bf16_f32 v203, v64, v65
	ds_write2_b32 v104, v202, v203 offset1:68
	v_mul_f32_e32 v252, v60, v65
	v_mul_f32_e32 v253, v60, v64
	v_fma_f32 v252, v62, v64, -v252
	v_fma_f32 v253, v62, v65, v253
	v_add_f32_e32 v64, v238, v252
	v_add_f32_e32 v65, v160, v253
	v_cvt_pk_bf16_f32 v202, v64, v65
	v_mul_f32_e32 v252, v60, v65
	v_mul_f32_e32 v253, v60, v64
	v_fma_f32 v252, v62, v64, -v252
	v_fma_f32 v253, v62, v65, v253
	v_add_f32_e32 v64, v239, v252
	v_add_f32_e32 v65, v161, v253
	v_cvt_pk_bf16_f32 v203, v64, v65
	ds_write2_b32 v104, v202, v203 offset0:136 offset1:204
	s_waitcnt lgkmcnt(4)
	v_mul_f32_e32 v252, v60, v65
	v_mul_f32_e32 v253, v60, v64
	v_fma_f32 v252, v62, v64, -v252
	v_fma_f32 v253, v62, v65, v253
	v_add_f32_e32 v64, v240, v252
	v_add_f32_e32 v65, v162, v253
	v_cvt_pk_bf16_f32 v202, v64, v65
	v_mul_f32_e32 v252, v60, v65
	v_mul_f32_e32 v253, v60, v64
	v_fma_f32 v252, v62, v64, -v252
	v_fma_f32 v253, v62, v65, v253
	v_add_f32_e32 v64, v241, v252
	v_add_f32_e32 v65, v163, v253
	v_cvt_pk_bf16_f32 v203, v64, v65
	ds_write2_b32 v105, v202, v203 offset0:16 offset1:84
	v_mul_f32_e32 v252, v60, v65
	v_mul_f32_e32 v253, v60, v64
	v_fma_f32 v252, v62, v64, -v252
	v_fma_f32 v253, v62, v65, v253
	v_add_f32_e32 v64, v242, v252
	v_add_f32_e32 v65, v164, v253
	v_cvt_pk_bf16_f32 v202, v64, v65
	v_mul_f32_e32 v252, v60, v65
	v_mul_f32_e32 v253, v60, v64
	v_fma_f32 v252, v62, v64, -v252
	v_fma_f32 v253, v62, v65, v253
	v_add_f32_e32 v64, v243, v252
	v_add_f32_e32 v65, v165, v253
	v_cvt_pk_bf16_f32 v203, v64, v65
	ds_write2_b32 v105, v202, v203 offset0:152 offset1:220
	s_waitcnt lgkmcnt(5)
	v_mul_f32_e32 v252, v60, v65
	v_mul_f32_e32 v253, v60, v64
	v_fma_f32 v252, v62, v64, -v252
	v_fma_f32 v253, v62, v65, v253
	v_add_f32_e32 v64, v244, v252
	v_add_f32_e32 v65, v166, v253
	v_cvt_pk_bf16_f32 v202, v64, v65
	v_mul_f32_e32 v252, v60, v65
	v_mul_f32_e32 v253, v60, v64
	v_fma_f32 v252, v62, v64, -v252
	v_fma_f32 v253, v62, v65, v253
	v_add_f32_e32 v64, v245, v252
	v_add_f32_e32 v65, v167, v253
	v_cvt_pk_bf16_f32 v203, v64, v65
	ds_write2_b32 v106, v202, v203 offset0:32 offset1:100
	v_mul_f32_e32 v252, v60, v65
	v_mul_f32_e32 v253, v60, v64
	v_fma_f32 v252, v62, v64, -v252
	v_fma_f32 v253, v62, v65, v253
	v_add_f32_e32 v64, v246, v252
	v_add_f32_e32 v65, v168, v253
	v_cvt_pk_bf16_f32 v202, v64, v65
	v_mul_f32_e32 v252, v60, v65
	v_mul_f32_e32 v253, v60, v64
	v_fma_f32 v252, v62, v64, -v252
	v_fma_f32 v253, v62, v65, v253
	v_add_f32_e32 v64, v247, v252
	v_add_f32_e32 v65, v169, v253
	v_cvt_pk_bf16_f32 v203, v64, v65
	ds_write2_b32 v106, v202, v203 offset0:168 offset1:236
	s_waitcnt lgkmcnt(6)
	v_mul_f32_e32 v252, v60, v65
	v_mul_f32_e32 v253, v60, v64
	v_fma_f32 v252, v62, v64, -v252
	v_fma_f32 v253, v62, v65, v253
	v_add_f32_e32 v64, v248, v252
	v_add_f32_e32 v65, v170, v253
	v_cvt_pk_bf16_f32 v202, v64, v65
	v_mul_f32_e32 v252, v60, v65
	v_mul_f32_e32 v253, v60, v64
	v_fma_f32 v252, v62, v64, -v252
	v_fma_f32 v253, v62, v65, v253
	v_add_f32_e32 v64, v249, v252
	v_add_f32_e32 v65, v171, v253
	v_cvt_pk_bf16_f32 v203, v64, v65
	ds_write2_b32 v107, v202, v203 offset0:48 offset1:116
	v_mul_f32_e32 v252, v60, v65
	v_mul_f32_e32 v253, v60, v64
	v_fma_f32 v252, v62, v64, -v252
	v_fma_f32 v253, v62, v65, v253
	v_add_f32_e32 v64, v250, v252
	v_add_f32_e32 v65, v172, v253
	v_cvt_pk_bf16_f32 v202, v64, v65
	v_mul_f32_e32 v252, v60, v65
	v_mul_f32_e32 v253, v60, v64
	v_fma_f32 v252, v62, v64, -v252
	v_fma_f32 v253, v62, v65, v253
	v_add_f32_e32 v64, v251, v252
	v_add_f32_e32 v65, v173, v253
	v_cvt_pk_bf16_f32 v203, v64, v65
	ds_write2_b32 v107, v202, v203 offset0:184 offset1:252
	s_cmp_lt_i32 s34, 0
	s_cselect_b64 s[4:5], -1, 0
	s_xor_b64 s[2:3], s[0:1], -1
	s_and_b64 s[4:5], s[2:3], s[4:5]
	s_and_b64 vcc, exec, s[4:5]
	s_waitcnt lgkmcnt(0)
	ds_read_b128 v[20:23], v99 offset:9216
	ds_read_b128 v[108:111], v99 offset:9280
	s_waitcnt lgkmcnt(1)
	v_mfma_f32_16x16x32_bf16 v[20:23], v[0:3], v[20:23], 0
	s_waitcnt lgkmcnt(0)
	v_mfma_f32_16x16x32_bf16 v[20:23], v[4:7], v[108:111], v[20:23]
	ds_read_b128 v[108:111], v99 offset:9344
	ds_read_b128 v[112:115], v99 offset:9408
	s_waitcnt lgkmcnt(1)
	v_mfma_f32_16x16x32_bf16 v[20:23], v[8:11], v[108:111], v[20:23]
	s_waitcnt lgkmcnt(0)
	v_mfma_f32_16x16x32_bf16 v[20:23], v[12:15], v[112:115], v[20:23]
	s_cbranch_vccnz .LBB0_919
	v_lshlrev_b32_e32 v92, 16, v91
	v_and_b32_e32 v93, 0xffff0000, v91
	s_nop 4
	v_pk_fma_f32 v[22:23], v[18:19], v[92:93], v[22:23]
	s_cmp_lg_u32 s34, -1
	v_mul_f32_e32 v91, 0x3d372713, v23
	v_mul_f32_e32 v91, v23, v91
	v_fma_f32 v91, v23, v91, v23
	v_mul_f32_e32 v91, 0x3fcc422a, v91
	v_mul_f32_e32 v91, 0xbfb8aa3b, v91
	v_exp_f32_e32 v91, v91
	s_cselect_b32 s4, s35, 0x8000
	v_add_f32_e32 v91, 1.0, v91
	v_rcp_f32_e32 v93, v91
	v_mul_f32_e32 v91, 0x3d372713, v22
	v_mul_f32_e32 v91, v22, v91
	v_fma_f32 v91, v22, v91, v22
	v_mul_f32_e32 v91, 0x3fcc422a, v91
	v_mul_f32_e32 v91, 0xbfb8aa3b, v91
	v_exp_f32_e32 v91, v91
	s_nop 0
	v_add_f32_e32 v91, 1.0, v91
	v_rcp_f32_e32 v92, v91
	s_nop 0
	v_pk_mul_f32 v[22:23], v[22:23], v[92:93]
	v_lshlrev_b32_e32 v92, 16, v90
	v_and_b32_e32 v93, 0xffff0000, v90
	v_pk_fma_f32 v[20:21], v[16:17], v[92:93], v[20:21]
	s_nop 0
	v_mul_f32_e32 v90, 0x3d372713, v21
	v_mul_f32_e32 v90, v21, v90
	v_fma_f32 v90, v21, v90, v21
	v_mul_f32_e32 v90, 0x3fcc422a, v90
	v_mul_f32_e32 v90, 0xbfb8aa3b, v90
	v_exp_f32_e32 v90, v90
	s_nop 0
	v_add_f32_e32 v90, 1.0, v90
	v_rcp_f32_e32 v91, v90
	v_mul_f32_e32 v90, 0x3d372713, v20
	v_mul_f32_e32 v90, v20, v90
	v_fma_f32 v90, v20, v90, v20
	v_mul_f32_e32 v90, 0x3fcc422a, v90
	v_mul_f32_e32 v90, 0xbfb8aa3b, v90
	v_exp_f32_e32 v90, v90
	s_nop 0
	v_add_f32_e32 v90, 1.0, v90
	v_rcp_f32_e32 v90, v90
	s_nop 0
	v_pk_mul_f32 v[20:21], v[20:21], v[90:91]
	v_or_b32_e32 v90, s4, v121
	v_ashrrev_i32_e32 v91, 31, v90
	v_lshlrev_b64 v[90:91], 10, v[90:91]
	v_lshl_add_u64 v[90:91], v[26:27], 0, v[90:91]
	v_cvt_pk_bf16_f32 v20, v20, v21
	v_cvt_pk_bf16_f32 v21, v22, v23
	global_store_dwordx2 v[90:91], v[20:21], off
.LBB0_919:
	ds_write2_b32 v96, v204, v208 offset1:16
	ds_write2_b32 v96, v205, v209 offset0:36 offset1:52
	ds_write2_b32 v96, v206, v210 offset0:72 offset1:88
	ds_write2_b32 v96, v207, v211 offset0:108 offset1:124
	ds_write2_b32 v100, v212, v216 offset0:64 offset1:80
	ds_write2_b32 v100, v213, v217 offset0:100 offset1:116
	ds_write2_b32 v100, v214, v218 offset0:136 offset1:152
	ds_write2_b32 v100, v215, v219 offset0:172 offset1:188
	ds_write2_b32 v101, v220, v224 offset0:128 offset1:144
	ds_write2_b32 v101, v221, v225 offset0:164 offset1:180
	ds_write2_b32 v101, v222, v226 offset0:200 offset1:216
	ds_write2_b32 v101, v223, v227 offset0:236 offset1:252
	ds_write2_b32 v102, v228, v232 offset0:192 offset1:208
	ds_write2_b32 v102, v229, v233 offset0:228 offset1:244
	ds_write2_b32 v103, v230, v234 offset0:8 offset1:24
	ds_write2_b32 v103, v231, v235 offset0:44 offset1:60
	s_nop 1
	v_mfma_f32_16x16x16_bf16 v[204:207], v[28:29], v[78:79], 0
	v_mfma_f32_16x16x16_bf16 v[208:211], v[30:31], v[78:79], 0
	v_mfma_f32_16x16x16_bf16 v[212:215], v[66:67], v[78:79], 0
	v_mfma_f32_16x16x16_bf16 v[216:219], v[68:69], v[78:79], 0
	v_mfma_f32_16x16x16_bf16 v[220:223], v[70:71], v[78:79], 0
	v_mfma_f32_16x16x16_bf16 v[224:227], v[72:73], v[78:79], 0
	v_mfma_f32_16x16x16_bf16 v[228:231], v[74:75], v[78:79], 0
	v_mfma_f32_16x16x16_bf16 v[232:235], v[76:77], v[78:79], 0
	s_waitcnt lgkmcnt(0)
	ds_read_b128 v[236:239], v49
	ds_read_b128 v[240:243], v49 offset:16
	ds_read_b128 v[244:247], v49 offset:32
	ds_read_b128 v[248:251], v49 offset:48
	ds_read_b128 v[158:161], v49 offset:64
	ds_read_b128 v[162:165], v49 offset:80
	ds_read_b128 v[166:169], v49 offset:96
	ds_read_b128 v[170:173], v49 offset:112
	s_waitcnt lgkmcnt(3)
	v_mul_f32_e32 v252, v60, v65
	v_mul_f32_e32 v253, v60, v64
	v_fma_f32 v252, v62, v64, -v252
	v_fma_f32 v253, v62, v65, v253
	v_add_f32_e32 v64, v236, v252
	v_add_f32_e32 v65, v158, v253
	v_cvt_pk_bf16_f32 v202, v64, v65
	v_mul_f32_e32 v252, v60, v65
	v_mul_f32_e32 v253, v60, v64
	v_fma_f32 v252, v62, v64, -v252
	v_fma_f32 v253, v62, v65, v253
	v_add_f32_e32 v64, v237, v252
	v_add_f32_e32 v65, v159, v253
	v_cvt_pk_bf16_f32 v203, v64, v65
	ds_write2_b32 v104, v202, v203 offset1:68
	v_mul_f32_e32 v252, v60, v65
	v_mul_f32_e32 v253, v60, v64
	v_fma_f32 v252, v62, v64, -v252
	v_fma_f32 v253, v62, v65, v253
	v_add_f32_e32 v64, v238, v252
	v_add_f32_e32 v65, v160, v253
	v_cvt_pk_bf16_f32 v202, v64, v65
	v_mul_f32_e32 v252, v60, v65
	v_mul_f32_e32 v253, v60, v64
	v_fma_f32 v252, v62, v64, -v252
	v_fma_f32 v253, v62, v65, v253
	v_add_f32_e32 v64, v239, v252
	v_add_f32_e32 v65, v161, v253
	v_cvt_pk_bf16_f32 v203, v64, v65
	ds_write2_b32 v104, v202, v203 offset0:136 offset1:204
	s_waitcnt lgkmcnt(4)
	v_mul_f32_e32 v252, v60, v65
	v_mul_f32_e32 v253, v60, v64
	v_fma_f32 v252, v62, v64, -v252
	v_fma_f32 v253, v62, v65, v253
	v_add_f32_e32 v64, v240, v252
	v_add_f32_e32 v65, v162, v253
	v_cvt_pk_bf16_f32 v202, v64, v65
	v_mul_f32_e32 v252, v60, v65
	v_mul_f32_e32 v253, v60, v64
	v_fma_f32 v252, v62, v64, -v252
	v_fma_f32 v253, v62, v65, v253
	v_add_f32_e32 v64, v241, v252
	v_add_f32_e32 v65, v163, v253
	v_cvt_pk_bf16_f32 v203, v64, v65
	ds_write2_b32 v105, v202, v203 offset0:16 offset1:84
	v_mul_f32_e32 v252, v60, v65
	v_mul_f32_e32 v253, v60, v64
	v_fma_f32 v252, v62, v64, -v252
	v_fma_f32 v253, v62, v65, v253
	v_add_f32_e32 v64, v242, v252
	v_add_f32_e32 v65, v164, v253
	v_cvt_pk_bf16_f32 v202, v64, v65
	v_mul_f32_e32 v252, v60, v65
	v_mul_f32_e32 v253, v60, v64
	v_fma_f32 v252, v62, v64, -v252
	v_fma_f32 v253, v62, v65, v253
	v_add_f32_e32 v64, v243, v252
	v_add_f32_e32 v65, v165, v253
	v_cvt_pk_bf16_f32 v203, v64, v65
	ds_write2_b32 v105, v202, v203 offset0:152 offset1:220
	s_waitcnt lgkmcnt(5)
	v_mul_f32_e32 v252, v60, v65
	v_mul_f32_e32 v253, v60, v64
	v_fma_f32 v252, v62, v64, -v252
	v_fma_f32 v253, v62, v65, v253
	v_add_f32_e32 v64, v244, v252
	v_add_f32_e32 v65, v166, v253
	v_cvt_pk_bf16_f32 v202, v64, v65
	v_mul_f32_e32 v252, v60, v65
	v_mul_f32_e32 v253, v60, v64
	v_fma_f32 v252, v62, v64, -v252
	v_fma_f32 v253, v62, v65, v253
	v_add_f32_e32 v64, v245, v252
	v_add_f32_e32 v65, v167, v253
	v_cvt_pk_bf16_f32 v203, v64, v65
	ds_write2_b32 v106, v202, v203 offset0:32 offset1:100
	v_mul_f32_e32 v252, v60, v65
	v_mul_f32_e32 v253, v60, v64
	v_fma_f32 v252, v62, v64, -v252
	v_fma_f32 v253, v62, v65, v253
	v_add_f32_e32 v64, v246, v252
	v_add_f32_e32 v65, v168, v253
	v_cvt_pk_bf16_f32 v202, v64, v65
	v_mul_f32_e32 v252, v60, v65
	v_mul_f32_e32 v253, v60, v64
	v_fma_f32 v252, v62, v64, -v252
	v_fma_f32 v253, v62, v65, v253
	v_add_f32_e32 v64, v247, v252
	v_add_f32_e32 v65, v169, v253
	v_cvt_pk_bf16_f32 v203, v64, v65
	ds_write2_b32 v106, v202, v203 offset0:168 offset1:236
	s_waitcnt lgkmcnt(6)
	v_mul_f32_e32 v252, v60, v65
	v_mul_f32_e32 v253, v60, v64
	v_fma_f32 v252, v62, v64, -v252
	v_fma_f32 v253, v62, v65, v253
	v_add_f32_e32 v64, v248, v252
	v_add_f32_e32 v65, v170, v253
	v_cvt_pk_bf16_f32 v202, v64, v65
	v_mul_f32_e32 v252, v60, v65
	v_mul_f32_e32 v253, v60, v64
	v_fma_f32 v252, v62, v64, -v252
	v_fma_f32 v253, v62, v65, v253
	v_add_f32_e32 v64, v249, v252
	v_add_f32_e32 v65, v171, v253
	v_cvt_pk_bf16_f32 v203, v64, v65
	ds_write2_b32 v107, v202, v203 offset0:48 offset1:116
	v_mul_f32_e32 v252, v60, v65
	v_mul_f32_e32 v253, v60, v64
	v_fma_f32 v252, v62, v64, -v252
	v_fma_f32 v253, v62, v65, v253
	v_add_f32_e32 v64, v250, v252
	v_add_f32_e32 v65, v172, v253
	v_cvt_pk_bf16_f32 v202, v64, v65
	v_mul_f32_e32 v252, v60, v65
	v_mul_f32_e32 v253, v60, v64
	v_fma_f32 v252, v62, v64, -v252
	v_fma_f32 v253, v62, v65, v253
	v_add_f32_e32 v64, v251, v252
	v_add_f32_e32 v65, v173, v253
	v_cvt_pk_bf16_f32 v203, v64, v65
	ds_write2_b32 v107, v202, v203 offset0:184 offset1:252
	s_cmp_lt_i32 s34, -1
	s_cselect_b64 s[4:5], -1, 0
	s_and_b64 s[4:5], s[2:3], s[4:5]
	s_and_b64 vcc, exec, s[4:5]
	s_waitcnt lgkmcnt(0)
	ds_read_b128 v[20:23], v99 offset:9216
	ds_read_b128 v[90:93], v99 offset:9280
	s_waitcnt lgkmcnt(1)
	v_mfma_f32_16x16x32_bf16 v[20:23], v[0:3], v[20:23], 0
	s_waitcnt lgkmcnt(0)
	v_mfma_f32_16x16x32_bf16 v[20:23], v[4:7], v[90:93], v[20:23]
	ds_read_b128 v[90:93], v99 offset:9344
	ds_read_b128 v[108:111], v99 offset:9408
	s_waitcnt lgkmcnt(1)
	v_mfma_f32_16x16x32_bf16 v[20:23], v[8:11], v[90:93], v[20:23]
	s_waitcnt lgkmcnt(0)
	v_mfma_f32_16x16x32_bf16 v[20:23], v[12:15], v[108:111], v[20:23]
	s_cbranch_vccnz .LBB0_921
	v_lshlrev_b32_e32 v90, 16, v89
	v_and_b32_e32 v91, 0xffff0000, v89
	s_nop 4
	v_pk_fma_f32 v[22:23], v[18:19], v[90:91], v[22:23]
	s_add_i32 s4, s35, 16
	v_mul_f32_e32 v89, 0x3d372713, v23
	v_mul_f32_e32 v89, v23, v89
	v_fma_f32 v89, v23, v89, v23
	v_mul_f32_e32 v89, 0x3fcc422a, v89
	v_mul_f32_e32 v89, 0xbfb8aa3b, v89
	v_exp_f32_e32 v89, v89
	s_cmp_lg_u32 s34, -2
	s_cselect_b32 s4, s4, 0x8000
	v_add_f32_e32 v89, 1.0, v89
	v_rcp_f32_e32 v91, v89
	v_mul_f32_e32 v89, 0x3d372713, v22
	v_mul_f32_e32 v89, v22, v89
	v_fma_f32 v89, v22, v89, v22
	v_mul_f32_e32 v89, 0x3fcc422a, v89
	v_mul_f32_e32 v89, 0xbfb8aa3b, v89
	v_exp_f32_e32 v89, v89
	s_nop 0
	v_add_f32_e32 v89, 1.0, v89
	v_rcp_f32_e32 v90, v89
	s_nop 0
	v_pk_mul_f32 v[22:23], v[22:23], v[90:91]
	v_lshlrev_b32_e32 v90, 16, v88
	v_and_b32_e32 v91, 0xffff0000, v88
	v_pk_fma_f32 v[20:21], v[16:17], v[90:91], v[20:21]
	s_nop 0
	v_mul_f32_e32 v88, 0x3d372713, v21
	v_mul_f32_e32 v88, v21, v88
	v_fma_f32 v88, v21, v88, v21
	v_mul_f32_e32 v88, 0x3fcc422a, v88
	v_mul_f32_e32 v88, 0xbfb8aa3b, v88
	v_exp_f32_e32 v88, v88
	s_nop 0
	v_add_f32_e32 v88, 1.0, v88
	v_rcp_f32_e32 v89, v88
	v_mul_f32_e32 v88, 0x3d372713, v20
	v_mul_f32_e32 v88, v20, v88
	v_fma_f32 v88, v20, v88, v20
	v_mul_f32_e32 v88, 0x3fcc422a, v88
	v_mul_f32_e32 v88, 0xbfb8aa3b, v88
	v_exp_f32_e32 v88, v88
	s_nop 0
	v_add_f32_e32 v88, 1.0, v88
	v_rcp_f32_e32 v88, v88
	s_nop 0
	v_pk_mul_f32 v[20:21], v[20:21], v[88:89]
	v_or_b32_e32 v88, s4, v121
	v_ashrrev_i32_e32 v89, 31, v88
	v_lshlrev_b64 v[88:89], 10, v[88:89]
	v_lshl_add_u64 v[88:89], v[26:27], 0, v[88:89]
	v_cvt_pk_bf16_f32 v20, v20, v21
	v_cvt_pk_bf16_f32 v21, v22, v23
	global_store_dwordx2 v[88:89], v[20:21], off
.LBB0_921:
	ds_write2_b32 v96, v204, v208 offset1:16
	ds_write2_b32 v96, v205, v209 offset0:36 offset1:52
	ds_write2_b32 v96, v206, v210 offset0:72 offset1:88
	ds_write2_b32 v96, v207, v211 offset0:108 offset1:124
	ds_write2_b32 v100, v212, v216 offset0:64 offset1:80
	ds_write2_b32 v100, v213, v217 offset0:100 offset1:116
	ds_write2_b32 v100, v214, v218 offset0:136 offset1:152
	ds_write2_b32 v100, v215, v219 offset0:172 offset1:188
	ds_write2_b32 v101, v220, v224 offset0:128 offset1:144
	ds_write2_b32 v101, v221, v225 offset0:164 offset1:180
	ds_write2_b32 v101, v222, v226 offset0:200 offset1:216
	ds_write2_b32 v101, v223, v227 offset0:236 offset1:252
	ds_write2_b32 v102, v228, v232 offset0:192 offset1:208
	ds_write2_b32 v102, v229, v233 offset0:228 offset1:244
	ds_write2_b32 v103, v230, v234 offset0:8 offset1:24
	ds_write2_b32 v103, v231, v235 offset0:44 offset1:60
	s_waitcnt lgkmcnt(0)
	ds_read_b128 v[236:239], v49
	ds_read_b128 v[240:243], v49 offset:16
	ds_read_b128 v[244:247], v49 offset:32
	ds_read_b128 v[248:251], v49 offset:48
	ds_read_b128 v[158:161], v49 offset:64
	ds_read_b128 v[162:165], v49 offset:80
	ds_read_b128 v[166:169], v49 offset:96
	ds_read_b128 v[170:173], v49 offset:112
	s_waitcnt lgkmcnt(3)
	v_mul_f32_e32 v252, v60, v65
	v_mul_f32_e32 v253, v60, v64
	v_fma_f32 v252, v62, v64, -v252
	v_fma_f32 v253, v62, v65, v253
	v_add_f32_e32 v64, v236, v252
	v_add_f32_e32 v65, v158, v253
	v_cvt_pk_bf16_f32 v202, v64, v65
	v_mul_f32_e32 v252, v60, v65
	v_mul_f32_e32 v253, v60, v64
	v_fma_f32 v252, v62, v64, -v252
	v_fma_f32 v253, v62, v65, v253
	v_add_f32_e32 v64, v237, v252
	v_add_f32_e32 v65, v159, v253
	v_cvt_pk_bf16_f32 v203, v64, v65
	ds_write2_b32 v104, v202, v203 offset1:68
	v_mul_f32_e32 v252, v60, v65
	v_mul_f32_e32 v253, v60, v64
	v_fma_f32 v252, v62, v64, -v252
	v_fma_f32 v253, v62, v65, v253
	v_add_f32_e32 v64, v238, v252
	v_add_f32_e32 v65, v160, v253
	v_cvt_pk_bf16_f32 v202, v64, v65
	v_mul_f32_e32 v252, v60, v65
	v_mul_f32_e32 v253, v60, v64
	v_fma_f32 v252, v62, v64, -v252
	v_fma_f32 v253, v62, v65, v253
	v_add_f32_e32 v64, v239, v252
	v_add_f32_e32 v65, v161, v253
	v_cvt_pk_bf16_f32 v203, v64, v65
	ds_write2_b32 v104, v202, v203 offset0:136 offset1:204
	s_waitcnt lgkmcnt(4)
	v_mul_f32_e32 v252, v60, v65
	v_mul_f32_e32 v253, v60, v64
	v_fma_f32 v252, v62, v64, -v252
	v_fma_f32 v253, v62, v65, v253
	v_add_f32_e32 v64, v240, v252
	v_add_f32_e32 v65, v162, v253
	v_cvt_pk_bf16_f32 v202, v64, v65
	v_mul_f32_e32 v252, v60, v65
	v_mul_f32_e32 v253, v60, v64
	v_fma_f32 v252, v62, v64, -v252
	v_fma_f32 v253, v62, v65, v253
	v_add_f32_e32 v64, v241, v252
	v_add_f32_e32 v65, v163, v253
	v_cvt_pk_bf16_f32 v203, v64, v65
	ds_write2_b32 v105, v202, v203 offset0:16 offset1:84
	v_mul_f32_e32 v252, v60, v65
	v_mul_f32_e32 v253, v60, v64
	v_fma_f32 v252, v62, v64, -v252
	v_fma_f32 v253, v62, v65, v253
	v_add_f32_e32 v64, v242, v252
	v_add_f32_e32 v65, v164, v253
	v_cvt_pk_bf16_f32 v202, v64, v65
	v_mul_f32_e32 v252, v60, v65
	v_mul_f32_e32 v253, v60, v64
	v_fma_f32 v252, v62, v64, -v252
	v_fma_f32 v253, v62, v65, v253
	v_add_f32_e32 v64, v243, v252
	v_add_f32_e32 v65, v165, v253
	v_cvt_pk_bf16_f32 v203, v64, v65
	ds_write2_b32 v105, v202, v203 offset0:152 offset1:220
	s_waitcnt lgkmcnt(5)
	v_mul_f32_e32 v252, v60, v65
	v_mul_f32_e32 v253, v60, v64
	v_fma_f32 v252, v62, v64, -v252
	v_fma_f32 v253, v62, v65, v253
	v_add_f32_e32 v64, v244, v252
	v_add_f32_e32 v65, v166, v253
	v_cvt_pk_bf16_f32 v202, v64, v65
	v_mul_f32_e32 v252, v60, v65
	v_mul_f32_e32 v253, v60, v64
	v_fma_f32 v252, v62, v64, -v252
	v_fma_f32 v253, v62, v65, v253
	v_add_f32_e32 v64, v245, v252
	v_add_f32_e32 v65, v167, v253
	v_cvt_pk_bf16_f32 v203, v64, v65
	ds_write2_b32 v106, v202, v203 offset0:32 offset1:100
	v_mul_f32_e32 v252, v60, v65
	v_mul_f32_e32 v253, v60, v64
	v_fma_f32 v252, v62, v64, -v252
	v_fma_f32 v253, v62, v65, v253
	v_add_f32_e32 v64, v246, v252
	v_add_f32_e32 v65, v168, v253
	v_cvt_pk_bf16_f32 v202, v64, v65
	v_mul_f32_e32 v252, v60, v65
	v_mul_f32_e32 v253, v60, v64
	v_fma_f32 v252, v62, v64, -v252
	v_fma_f32 v253, v62, v65, v253
	v_add_f32_e32 v64, v247, v252
	v_add_f32_e32 v65, v169, v253
	v_cvt_pk_bf16_f32 v203, v64, v65
	ds_write2_b32 v106, v202, v203 offset0:168 offset1:236
	s_waitcnt lgkmcnt(6)
	v_mul_f32_e32 v252, v60, v65
	v_mul_f32_e32 v253, v60, v64
	v_fma_f32 v252, v62, v64, -v252
	v_fma_f32 v253, v62, v65, v253
	v_add_f32_e32 v64, v248, v252
	v_add_f32_e32 v65, v170, v253
	v_cvt_pk_bf16_f32 v202, v64, v65
	v_mul_f32_e32 v252, v60, v65
	v_mul_f32_e32 v253, v60, v64
	v_fma_f32 v252, v62, v64, -v252
	v_fma_f32 v253, v62, v65, v253
	v_add_f32_e32 v64, v249, v252
	v_add_f32_e32 v65, v171, v253
	v_cvt_pk_bf16_f32 v203, v64, v65
	ds_write2_b32 v107, v202, v203 offset0:48 offset1:116
	v_mul_f32_e32 v252, v60, v65
	v_mul_f32_e32 v253, v60, v64
	v_fma_f32 v252, v62, v64, -v252
	v_fma_f32 v253, v62, v65, v253
	v_add_f32_e32 v64, v250, v252
	v_add_f32_e32 v65, v172, v253
	v_cvt_pk_bf16_f32 v202, v64, v65
	v_mul_f32_e32 v252, v60, v65
	v_mul_f32_e32 v253, v60, v64
	v_fma_f32 v252, v62, v64, -v252
	v_fma_f32 v253, v62, v65, v253
	v_add_f32_e32 v64, v251, v252
	v_add_f32_e32 v65, v173, v253
	v_cvt_pk_bf16_f32 v203, v64, v65
	ds_write2_b32 v107, v202, v203 offset0:184 offset1:252
	s_cmp_lt_i32 s34, -2
	s_cselect_b64 s[4:5], -1, 0
	s_and_b64 s[2:3], s[2:3], s[4:5]
	s_and_b64 vcc, exec, s[2:3]
	s_waitcnt lgkmcnt(0)
	ds_read_b128 v[20:23], v99 offset:9216
	ds_read_b128 v[88:91], v99 offset:9280
	s_waitcnt lgkmcnt(1)
	v_mfma_f32_16x16x32_bf16 v[20:23], v[0:3], v[20:23], 0
	s_waitcnt lgkmcnt(0)
	v_mfma_f32_16x16x32_bf16 v[20:23], v[4:7], v[88:91], v[20:23]
	ds_read_b128 v[88:91], v99 offset:9344
	ds_read_b128 v[108:111], v99 offset:9408
	s_waitcnt lgkmcnt(1)
	v_mfma_f32_16x16x32_bf16 v[20:23], v[8:11], v[88:91], v[20:23]
	s_waitcnt lgkmcnt(0)
	v_mfma_f32_16x16x32_bf16 v[20:23], v[12:15], v[108:111], v[20:23]
	s_cbranch_vccnz .LBB0_914
	v_lshlrev_b32_e32 v88, 16, v79
	v_and_b32_e32 v89, 0xffff0000, v79
	s_nop 4
	v_pk_fma_f32 v[22:23], v[18:19], v[88:89], v[22:23]
	s_add_i32 s2, s35, 32
	v_mul_f32_e32 v79, 0x3d372713, v23
	v_mul_f32_e32 v79, v23, v79
	v_fma_f32 v79, v23, v79, v23
	v_mul_f32_e32 v79, 0x3fcc422a, v79
	v_mul_f32_e32 v79, 0xbfb8aa3b, v79
	v_exp_f32_e32 v79, v79
	s_cmp_lg_u32 s34, -3
	s_cselect_b32 s2, s2, 0x8000
	v_add_f32_e32 v79, 1.0, v79
	v_rcp_f32_e32 v89, v79
	v_mul_f32_e32 v79, 0x3d372713, v22
	v_mul_f32_e32 v79, v22, v79
	v_fma_f32 v79, v22, v79, v22
	v_mul_f32_e32 v79, 0x3fcc422a, v79
	v_mul_f32_e32 v79, 0xbfb8aa3b, v79
	v_exp_f32_e32 v79, v79
	s_nop 0
	v_add_f32_e32 v79, 1.0, v79
	v_rcp_f32_e32 v88, v79
	s_nop 0
	v_pk_mul_f32 v[22:23], v[22:23], v[88:89]
	v_lshlrev_b32_e32 v88, 16, v78
	v_and_b32_e32 v89, 0xffff0000, v78
	v_pk_fma_f32 v[20:21], v[16:17], v[88:89], v[20:21]
	s_nop 0
	v_mul_f32_e32 v78, 0x3d372713, v21
	v_mul_f32_e32 v78, v21, v78
	v_fma_f32 v78, v21, v78, v21
	v_mul_f32_e32 v78, 0x3fcc422a, v78
	v_mul_f32_e32 v78, 0xbfb8aa3b, v78
	v_exp_f32_e32 v78, v78
	s_nop 0
	v_add_f32_e32 v78, 1.0, v78
	v_rcp_f32_e32 v79, v78
	v_mul_f32_e32 v78, 0x3d372713, v20
	v_mul_f32_e32 v78, v20, v78
	v_fma_f32 v78, v20, v78, v20
	v_mul_f32_e32 v78, 0x3fcc422a, v78
	v_mul_f32_e32 v78, 0xbfb8aa3b, v78
	v_exp_f32_e32 v78, v78
	s_nop 0
	v_add_f32_e32 v78, 1.0, v78
	v_rcp_f32_e32 v78, v78
	s_nop 0
	v_pk_mul_f32 v[20:21], v[20:21], v[78:79]
	v_or_b32_e32 v78, s2, v121
	v_ashrrev_i32_e32 v79, 31, v78
	v_lshlrev_b64 v[78:79], 10, v[78:79]
	v_lshl_add_u64 v[78:79], v[26:27], 0, v[78:79]
	v_cvt_pk_bf16_f32 v20, v20, v21
	v_cvt_pk_bf16_f32 v21, v22, v23
	global_store_dwordx2 v[78:79], v[20:21], off
	s_branch .LBB0_914
